# P3 x preload: waves 1-7 load all 32 accumulator quads before grid barrier 3 (only wave 0, which runs the barrier protocol, loads after it)
# speedup vs baseline: 1.0423x; 1.0064x over previous
.LBB0_311:
	s_waitcnt vmcnt(0)
	s_waitcnt lgkmcnt(0)
	s_barrier
	s_cmpk_gt_u32 s2, 0xff
	s_cbranch_scc1 .Lxa_skip
	v_readfirstlane_b32 s4, v254
	s_and_b32 s5, s2, 7
	s_lshr_b32 s4, s4, 6
	s_lshl_b32 s5, s5, 3
	s_bfe_u32 s6, s2, 0x30003
	s_add_i32 s5, s5, s6
	s_lshr_b32 s6, s2, 6
	s_lshl_b32 s5, s5, 8
	s_lshr_b32 s7, s4, 2
	s_lshl_b32 s7, s7, 6
	s_add_i32 s5, s5, s7
	s_lshl_b32 s6, s6, 8
	s_and_b32 s7, s4, 3
	s_lshl_b32 s7, s7, 6
	s_add_i32 s6, s6, s7
	v_and_b32_e32 v200, 15, v254
	v_bfe_u32 v201, v254, 4, 2
	v_or_b32_e32 v200, s5, v200
	v_lshl_or_b32 v201, v201, 3, s6
	v_lshlrev_b32_e32 v200, 10, v200
	v_add_u32_e32 v200, v200, v201
	v_lshlrev_b32_e32 v200, 2, v200
	v_add_u32_e32 v201, 0x10000, v200
	v_add_u32_e32 v202, 0x20000, v200
	v_add_u32_e32 v203, 0x30000, v200
	v_add_u32_e32 v204, 0x80000, v200
	v_add_u32_e32 v205, 0x90000, v200
	v_add_u32_e32 v206, 0xa0000, v200
	v_add_u32_e32 v207, 0xb0000, v200
	s_cmp_eq_u32 s4, 0
	s_cbranch_scc1 .Lxa_w0
	global_load_dwordx4 v[124:127], v200, s[12:13] nt
	global_load_dwordx4 v[120:123], v200, s[12:13] offset:16 nt
	global_load_dwordx4 v[116:119], v200, s[12:13] offset:128 nt
	global_load_dwordx4 v[112:115], v200, s[12:13] offset:144 nt
	global_load_dwordx4 v[108:111], v201, s[12:13] nt
	global_load_dwordx4 v[104:107], v201, s[12:13] offset:16 nt
	global_load_dwordx4 v[100:103], v201, s[12:13] offset:128 nt
	global_load_dwordx4 v[96:99], v201, s[12:13] offset:144 nt
	global_load_dwordx4 v[92:95], v202, s[12:13] nt
	global_load_dwordx4 v[88:91], v202, s[12:13] offset:16 nt
	global_load_dwordx4 v[84:87], v202, s[12:13] offset:128 nt
	global_load_dwordx4 v[80:83], v202, s[12:13] offset:144 nt
	global_load_dwordx4 v[76:79], v203, s[12:13] nt
	global_load_dwordx4 v[72:75], v203, s[12:13] offset:16 nt
	global_load_dwordx4 v[68:71], v203, s[12:13] offset:128 nt
	global_load_dwordx4 v[64:67], v203, s[12:13] offset:144 nt
	global_load_dwordx4 v[60:63], v204, s[12:13] nt
	global_load_dwordx4 v[56:59], v204, s[12:13] offset:16 nt
	global_load_dwordx4 v[52:55], v204, s[12:13] offset:128 nt
	global_load_dwordx4 v[48:51], v204, s[12:13] offset:144 nt
	global_load_dwordx4 v[44:47], v205, s[12:13] nt
	global_load_dwordx4 v[40:43], v205, s[12:13] offset:16 nt
	global_load_dwordx4 v[36:39], v205, s[12:13] offset:128 nt
	global_load_dwordx4 v[32:35], v205, s[12:13] offset:144 nt
	global_load_dwordx4 v[28:31], v206, s[12:13] nt
	global_load_dwordx4 v[24:27], v206, s[12:13] offset:16 nt
	global_load_dwordx4 v[20:23], v206, s[12:13] offset:128 nt
	global_load_dwordx4 v[16:19], v206, s[12:13] offset:144 nt
	global_load_dwordx4 v[12:15], v207, s[12:13] nt
	global_load_dwordx4 v[8:11], v207, s[12:13] offset:16 nt
	global_load_dwordx4 v[4:7], v207, s[12:13] offset:128 nt
	global_load_dwordx4 v[0:3], v207, s[12:13] offset:144 nt
	s_branch .Lxa_skip
